# speedup vs baseline: 1.0210x; 1.0035x over previous
; DEVI int ltid() { int t = threadIdx.x; asm volatile("" : "+v"(t)); return t; }
; DEVI int lbid() { int t = blockIdx.x; asm volatile("" : "+s"(t)); return t; }
; DEVI int lgdim() { int t = gridDim.x; asm volatile("" : "+s"(t)); return t; }
; DEVI void norm_phase(const Params& p, int layer, int which, bool first) {
;     ...
;     for (size_t i = (size_t)lbid() * 512 + ltid(); i < 2 * n8; i += (size_t)lgdim() * 512) {
;       const bool second = i >= n8; const size_t j = second ? i - n8 : i;
;       const float* s = (second ? sv : su) + j * 8;
;       const f32x4 a = *(const f32x4*)s, b = *(const f32x4*)(s + 4);
;       if (second) {
;         unsigned w = 0;
;         w = __builtin_amdgcn_cvt_scalef32_pk_fp4_f32(w, a[0] * 4.25f, a[1] * 4.25f, 1.0f, 0);
;         w = __builtin_amdgcn_cvt_scalef32_pk_fp4_f32(w, a[2] * 4.25f, a[3] * 4.25f, 1.0f, 1);
;         w = __builtin_amdgcn_cvt_scalef32_pk_fp4_f32(w, b[0] * 4.25f, b[1] * 4.25f, 1.0f, 2);
;         w = __builtin_amdgcn_cvt_scalef32_pk_fp4_f32(w, b[2] * 4.25f, b[3] * 4.25f, 1.0f, 3);
;         *(unsigned*)(dv + j * 4) = w;
;       } else {
;         unsigned w = 0;
;         w = __builtin_amdgcn_cvt_scalef32_pk_fp4_f32(w, a[0] * 48.f, a[1] * 48.f, 1.0f, 0);
;         w = __builtin_amdgcn_cvt_scalef32_pk_fp4_f32(w, a[2] * 48.f, a[3] * 48.f, 1.0f, 1);
;         w = __builtin_amdgcn_cvt_scalef32_pk_fp4_f32(w, b[0] * 48.f, b[1] * 48.f, 1.0f, 2);
;         w = __builtin_amdgcn_cvt_scalef32_pk_fp4_f32(w, b[2] * 48.f, b[3] * 48.f, 1.0f, 3);
;         *(unsigned*)(du + j * 4) = w;
;       }
;     }
.LBB0_355:
	v_mov_b64_e32 v[104:105], v[2:3]
	s_mov_b64 s[0:1], 0x400000
	v_cmp_gt_u64_e32 vcc, s[0:1], v[104:105]
	s_and_saveexec_b64 s[24:25], vcc
	s_mov_b64 s[0:1], 0x1fffff
	v_cmp_lt_u64_e32 vcc, s[0:1], v[104:105]
	s_mov_b32 s0, 0xffe00000
	s_mov_b32 s1, -1
	v_lshl_add_u64 v[106:107], v[104:105], 0, s[0:1]
	v_cndmask_b32_e32 v108, v104, v106, vcc
	v_cndmask_b32_e32 v109, v105, v107, vcc
	v_mov_b32_e32 v106, s13
	v_mov_b32_e32 v107, s15
	v_cndmask_b32_e32 v111, v106, v107, vcc
	v_mov_b32_e32 v106, s12
	v_mov_b32_e32 v107, s14
	v_cndmask_b32_e32 v110, v106, v107, vcc
	v_lshl_add_u64 v[110:111], s[80:81], 2, v[110:111]
	v_lshlrev_b64 v[106:107], 5, v[108:109]
	v_lshl_add_u64 v[110:111], v[110:111], 0, v[106:107]
	global_load_dwordx4 v[44:47], v[110:111], off offset:16
	global_load_dwordx4 v[40:43], v[110:111], off
	s_mov_b64 exec, s[24:25]
	s_mov_b32 s0, s22
	s_ashr_i32 s1, s0, 31
	s_lshl_b64 s[0:1], s[0:1], 9
	v_lshl_add_u64 v[104:105], s[0:1], 0, v[104:105]
	s_mov_b64 s[0:1], 0x400000
	v_cmp_gt_u64_e32 vcc, s[0:1], v[104:105]
	s_and_saveexec_b64 s[24:25], vcc
	s_mov_b64 s[0:1], 0x1fffff
	v_cmp_lt_u64_e32 vcc, s[0:1], v[104:105]
	s_mov_b32 s0, 0xffe00000
	s_mov_b32 s1, -1
	v_lshl_add_u64 v[106:107], v[104:105], 0, s[0:1]
	v_cndmask_b32_e32 v108, v104, v106, vcc
	v_cndmask_b32_e32 v109, v105, v107, vcc
	v_mov_b32_e32 v106, s13
	v_mov_b32_e32 v107, s15
	v_cndmask_b32_e32 v111, v106, v107, vcc
	v_mov_b32_e32 v106, s12
	v_mov_b32_e32 v107, s14
	v_cndmask_b32_e32 v110, v106, v107, vcc
	v_lshl_add_u64 v[110:111], s[80:81], 2, v[110:111]
	v_lshlrev_b64 v[106:107], 5, v[108:109]
	v_lshl_add_u64 v[110:111], v[110:111], 0, v[106:107]
	global_load_dwordx4 v[52:55], v[110:111], off offset:16
	global_load_dwordx4 v[48:51], v[110:111], off
	s_mov_b64 exec, s[24:25]
	s_mov_b32 s0, s22
	s_ashr_i32 s1, s0, 31
	s_lshl_b64 s[0:1], s[0:1], 9
	v_lshl_add_u64 v[104:105], s[0:1], 0, v[104:105]
	s_mov_b64 s[0:1], 0x400000
	v_cmp_gt_u64_e32 vcc, s[0:1], v[104:105]
	s_and_saveexec_b64 s[24:25], vcc
	s_mov_b64 s[0:1], 0x1fffff
	v_cmp_lt_u64_e32 vcc, s[0:1], v[104:105]
	s_mov_b32 s0, 0xffe00000
	s_mov_b32 s1, -1
	v_lshl_add_u64 v[106:107], v[104:105], 0, s[0:1]
	v_cndmask_b32_e32 v108, v104, v106, vcc
	v_cndmask_b32_e32 v109, v105, v107, vcc
	v_mov_b32_e32 v106, s13
	v_mov_b32_e32 v107, s15
	v_cndmask_b32_e32 v111, v106, v107, vcc
	v_mov_b32_e32 v106, s12
	v_mov_b32_e32 v107, s14
	v_cndmask_b32_e32 v110, v106, v107, vcc
	v_lshl_add_u64 v[110:111], s[80:81], 2, v[110:111]
	v_lshlrev_b64 v[106:107], 5, v[108:109]
	v_lshl_add_u64 v[110:111], v[110:111], 0, v[106:107]
	global_load_dwordx4 v[60:63], v[110:111], off offset:16
	global_load_dwordx4 v[56:59], v[110:111], off
	s_mov_b64 exec, s[24:25]
	s_mov_b32 s0, s22
	s_ashr_i32 s1, s0, 31
	s_lshl_b64 s[0:1], s[0:1], 9
	v_lshl_add_u64 v[104:105], s[0:1], 0, v[104:105]
	s_mov_b64 s[0:1], 0x400000
	v_cmp_gt_u64_e32 vcc, s[0:1], v[104:105]
	s_and_saveexec_b64 s[24:25], vcc
	s_mov_b64 s[0:1], 0x1fffff
	v_cmp_lt_u64_e32 vcc, s[0:1], v[104:105]
	s_mov_b32 s0, 0xffe00000
	s_mov_b32 s1, -1
	v_lshl_add_u64 v[106:107], v[104:105], 0, s[0:1]
	v_cndmask_b32_e32 v108, v104, v106, vcc
	v_cndmask_b32_e32 v109, v105, v107, vcc
	v_mov_b32_e32 v106, s13
	v_mov_b32_e32 v107, s15
	v_cndmask_b32_e32 v111, v106, v107, vcc
	v_mov_b32_e32 v106, s12
	v_mov_b32_e32 v107, s14
	v_cndmask_b32_e32 v110, v106, v107, vcc
	v_lshl_add_u64 v[110:111], s[80:81], 2, v[110:111]
	v_lshlrev_b64 v[106:107], 5, v[108:109]
	v_lshl_add_u64 v[110:111], v[110:111], 0, v[106:107]
	global_load_dwordx4 v[68:71], v[110:111], off offset:16
	global_load_dwordx4 v[64:67], v[110:111], off
	s_mov_b64 exec, s[24:25]
	s_mov_b32 s0, s22
	s_ashr_i32 s1, s0, 31
	s_lshl_b64 s[0:1], s[0:1], 9
	v_lshl_add_u64 v[104:105], s[0:1], 0, v[104:105]
	s_mov_b64 s[0:1], 0x400000
	v_cmp_gt_u64_e32 vcc, s[0:1], v[104:105]
	s_and_saveexec_b64 s[24:25], vcc
	s_mov_b64 s[0:1], 0x1fffff
	v_cmp_lt_u64_e32 vcc, s[0:1], v[104:105]
	s_mov_b32 s0, 0xffe00000
	s_mov_b32 s1, -1
	v_lshl_add_u64 v[106:107], v[104:105], 0, s[0:1]
	v_cndmask_b32_e32 v108, v104, v106, vcc
	v_cndmask_b32_e32 v109, v105, v107, vcc
	v_mov_b32_e32 v106, s13
	v_mov_b32_e32 v107, s15
	v_cndmask_b32_e32 v111, v106, v107, vcc
	v_mov_b32_e32 v106, s12
	v_mov_b32_e32 v107, s14
	v_cndmask_b32_e32 v110, v106, v107, vcc
	v_lshl_add_u64 v[110:111], s[80:81], 2, v[110:111]
	v_lshlrev_b64 v[106:107], 5, v[108:109]
	v_lshl_add_u64 v[110:111], v[110:111], 0, v[106:107]
	global_load_dwordx4 v[76:79], v[110:111], off offset:16
	global_load_dwordx4 v[72:75], v[110:111], off
	s_mov_b64 exec, s[24:25]
	s_mov_b32 s0, s22
	s_ashr_i32 s1, s0, 31
	s_lshl_b64 s[0:1], s[0:1], 9
	v_lshl_add_u64 v[104:105], s[0:1], 0, v[104:105]
	s_mov_b64 s[0:1], 0x400000
	v_cmp_gt_u64_e32 vcc, s[0:1], v[104:105]
	s_and_saveexec_b64 s[24:25], vcc
	s_mov_b64 s[0:1], 0x1fffff
	v_cmp_lt_u64_e32 vcc, s[0:1], v[104:105]
	s_mov_b32 s0, 0xffe00000
	s_mov_b32 s1, -1
	v_lshl_add_u64 v[106:107], v[104:105], 0, s[0:1]
	v_cndmask_b32_e32 v108, v104, v106, vcc
	v_cndmask_b32_e32 v109, v105, v107, vcc
	v_mov_b32_e32 v106, s13
	v_mov_b32_e32 v107, s15
	v_cndmask_b32_e32 v111, v106, v107, vcc
	v_mov_b32_e32 v106, s12
	v_mov_b32_e32 v107, s14
	v_cndmask_b32_e32 v110, v106, v107, vcc
	v_lshl_add_u64 v[110:111], s[80:81], 2, v[110:111]
	v_lshlrev_b64 v[106:107], 5, v[108:109]
	v_lshl_add_u64 v[110:111], v[110:111], 0, v[106:107]
	global_load_dwordx4 v[84:87], v[110:111], off offset:16
	global_load_dwordx4 v[80:83], v[110:111], off
	s_mov_b64 exec, s[24:25]
	s_mov_b32 s0, s22
	s_ashr_i32 s1, s0, 31
	s_lshl_b64 s[0:1], s[0:1], 9
	v_lshl_add_u64 v[104:105], s[0:1], 0, v[104:105]
; DEVI int ltid() { int t = threadIdx.x; asm volatile("" : "+v"(t)); return t; }
; DEVI int lbid() { int t = blockIdx.x; asm volatile("" : "+s"(t)); return t; }
; DEVI int lgdim() { int t = gridDim.x; asm volatile("" : "+s"(t)); return t; }
; DEVI void norm_phase(const Params& p, int layer, int which, bool first) {
;     ...
;     for (size_t i = (size_t)lbid() * 512 + ltid(); i < 2 * n8; i += (size_t)lgdim() * 512) {
;       const bool second = i >= n8; const size_t j = second ? i - n8 : i;
;       const float* s = (second ? sv : su) + j * 8;
;       const f32x4 a = *(const f32x4*)s, b = *(const f32x4*)(s + 4);
;       if (second) {
;         unsigned w = 0;
;         w = __builtin_amdgcn_cvt_scalef32_pk_fp4_f32(w, a[0] * 4.25f, a[1] * 4.25f, 1.0f, 0);
;         w = __builtin_amdgcn_cvt_scalef32_pk_fp4_f32(w, a[2] * 4.25f, a[3] * 4.25f, 1.0f, 1);
;         w = __builtin_amdgcn_cvt_scalef32_pk_fp4_f32(w, b[0] * 4.25f, b[1] * 4.25f, 1.0f, 2);
;         w = __builtin_amdgcn_cvt_scalef32_pk_fp4_f32(w, b[2] * 4.25f, b[3] * 4.25f, 1.0f, 3);
;         *(unsigned*)(dv + j * 4) = w;
;       } else {
;         unsigned w = 0;
;         w = __builtin_amdgcn_cvt_scalef32_pk_fp4_f32(w, a[0] * 48.f, a[1] * 48.f, 1.0f, 0);
;         w = __builtin_amdgcn_cvt_scalef32_pk_fp4_f32(w, a[2] * 48.f, a[3] * 48.f, 1.0f, 1);
;         w = __builtin_amdgcn_cvt_scalef32_pk_fp4_f32(w, b[0] * 48.f, b[1] * 48.f, 1.0f, 2);
;         w = __builtin_amdgcn_cvt_scalef32_pk_fp4_f32(w, b[2] * 48.f, b[3] * 48.f, 1.0f, 3);
;         *(unsigned*)(du + j * 4) = w;
;       }
;     }
	s_mov_b64 s[0:1], 0x400000
	v_cmp_gt_u64_e32 vcc, s[0:1], v[104:105]
	s_and_saveexec_b64 s[24:25], vcc
	s_mov_b64 s[0:1], 0x1fffff
	v_cmp_lt_u64_e32 vcc, s[0:1], v[104:105]
	s_mov_b32 s0, 0xffe00000
	s_mov_b32 s1, -1
	v_lshl_add_u64 v[106:107], v[104:105], 0, s[0:1]
	v_cndmask_b32_e32 v108, v104, v106, vcc
	v_cndmask_b32_e32 v109, v105, v107, vcc
	v_mov_b32_e32 v106, s13
	v_mov_b32_e32 v107, s15
	v_cndmask_b32_e32 v111, v106, v107, vcc
	v_mov_b32_e32 v106, s12
	v_mov_b32_e32 v107, s14
	v_cndmask_b32_e32 v110, v106, v107, vcc
	v_lshl_add_u64 v[110:111], s[80:81], 2, v[110:111]
	v_lshlrev_b64 v[106:107], 5, v[108:109]
	v_lshl_add_u64 v[110:111], v[110:111], 0, v[106:107]
	global_load_dwordx4 v[92:95], v[110:111], off offset:16
	global_load_dwordx4 v[88:91], v[110:111], off
	s_mov_b64 exec, s[24:25]
	s_mov_b32 s0, s22
	s_ashr_i32 s1, s0, 31
	s_lshl_b64 s[0:1], s[0:1], 9
	v_lshl_add_u64 v[104:105], s[0:1], 0, v[104:105]
	s_mov_b64 s[0:1], 0x400000
	v_cmp_gt_u64_e32 vcc, s[0:1], v[104:105]
	s_and_saveexec_b64 s[24:25], vcc
	s_mov_b64 s[0:1], 0x1fffff
	v_cmp_lt_u64_e32 vcc, s[0:1], v[104:105]
	s_mov_b32 s0, 0xffe00000
	s_mov_b32 s1, -1
	v_lshl_add_u64 v[106:107], v[104:105], 0, s[0:1]
	v_cndmask_b32_e32 v108, v104, v106, vcc
	v_cndmask_b32_e32 v109, v105, v107, vcc
	v_mov_b32_e32 v106, s13
	v_mov_b32_e32 v107, s15
	v_cndmask_b32_e32 v111, v106, v107, vcc
	v_mov_b32_e32 v106, s12
	v_mov_b32_e32 v107, s14
	v_cndmask_b32_e32 v110, v106, v107, vcc
	v_lshl_add_u64 v[110:111], s[80:81], 2, v[110:111]
	v_lshlrev_b64 v[106:107], 5, v[108:109]
	v_lshl_add_u64 v[110:111], v[110:111], 0, v[106:107]
	global_load_dwordx4 v[100:103], v[110:111], off offset:16
	global_load_dwordx4 v[96:99], v[110:111], off
	s_mov_b64 exec, s[24:25]
	s_mov_b32 s0, s22
	s_ashr_i32 s1, s0, 31
	s_lshl_b64 s[0:1], s[0:1], 9
	v_lshl_add_u64 v[104:105], s[0:1], 0, v[104:105]
	s_waitcnt vmcnt(0)
	v_mov_b64_e32 v[104:105], v[2:3]
	s_mov_b64 s[0:1], 0x400000
	v_cmp_gt_u64_e32 vcc, s[0:1], v[104:105]
	s_and_saveexec_b64 s[24:25], vcc
	s_mov_b64 s[0:1], 0x1fffff
	v_cmp_lt_u64_e32 vcc, s[0:1], v[104:105]
	s_mov_b32 s0, 0xffe00000
	s_mov_b32 s1, -1
	v_lshl_add_u64 v[106:107], v[104:105], 0, s[0:1]
	v_cndmask_b32_e32 v108, v104, v106, vcc
	v_cndmask_b32_e32 v109, v105, v107, vcc
	v_mov_b32_e32 v106, 0x42400000
	v_mov_b32_e32 v107, 0x40880000
	v_cndmask_b32_e32 v112, v106, v107, vcc
	v_mov_b32_e32 v106, 0xf4e0000
	v_mov_b32_e32 v107, 0x114e0000
	v_cndmask_b32_e32 v106, v106, v107, vcc
	v_mov_b32_e32 v107, v1
	v_lshl_add_u64 v[114:115], s[18:19], 0, v[106:107]
	v_mul_f32_e32 v106, v40, v112
	v_mul_f32_e32 v107, v41, v112
	v_mov_b32_e32 v113, v1
	v_cvt_scalef32_pk_fp4_f32 v113, v106, v107, 1.0
	v_mul_f32_e32 v106, v42, v112
	v_mul_f32_e32 v107, v43, v112
	v_cvt_scalef32_pk_fp4_f32 v113, v106, v107, 1.0 op_sel:[0,0,1,0]
	v_mul_f32_e32 v106, v112, v44
	v_mul_f32_e32 v107, v112, v45
	v_cvt_scalef32_pk_fp4_f32 v113, v106, v107, 1.0 op_sel:[0,0,0,1]
	v_mul_f32_e32 v106, v112, v46
	v_mul_f32_e32 v107, v112, v47
	v_cvt_scalef32_pk_fp4_f32 v113, v106, v107, 1.0 op_sel:[0,0,1,1]
	v_lshl_add_u64 v[114:115], v[108:109], 2, v[114:115]
	global_store_dword v[114:115], v113, off
	s_mov_b64 exec, s[24:25]
	s_mov_b32 s0, s22
	s_ashr_i32 s1, s0, 31
	s_lshl_b64 s[0:1], s[0:1], 9
	v_lshl_add_u64 v[104:105], s[0:1], 0, v[104:105]
	s_mov_b64 s[0:1], 0x400000
	v_cmp_gt_u64_e32 vcc, s[0:1], v[104:105]
	s_and_saveexec_b64 s[24:25], vcc
	s_mov_b64 s[0:1], 0x1fffff
	v_cmp_lt_u64_e32 vcc, s[0:1], v[104:105]
	s_mov_b32 s0, 0xffe00000
	s_mov_b32 s1, -1
	v_lshl_add_u64 v[106:107], v[104:105], 0, s[0:1]
	v_cndmask_b32_e32 v108, v104, v106, vcc
	v_cndmask_b32_e32 v109, v105, v107, vcc
	v_mov_b32_e32 v106, 0x42400000
	v_mov_b32_e32 v107, 0x40880000
	v_cndmask_b32_e32 v112, v106, v107, vcc
	v_mov_b32_e32 v106, 0xf4e0000
	v_mov_b32_e32 v107, 0x114e0000
	v_cndmask_b32_e32 v106, v106, v107, vcc
	v_mov_b32_e32 v107, v1
	v_lshl_add_u64 v[114:115], s[18:19], 0, v[106:107]
	v_mul_f32_e32 v106, v48, v112
	v_mul_f32_e32 v107, v49, v112
	v_mov_b32_e32 v113, v1
	v_cvt_scalef32_pk_fp4_f32 v113, v106, v107, 1.0
	v_mul_f32_e32 v106, v50, v112
	v_mul_f32_e32 v107, v51, v112
	v_cvt_scalef32_pk_fp4_f32 v113, v106, v107, 1.0 op_sel:[0,0,1,0]
	v_mul_f32_e32 v106, v112, v52
	v_mul_f32_e32 v107, v112, v53
	v_cvt_scalef32_pk_fp4_f32 v113, v106, v107, 1.0 op_sel:[0,0,0,1]
	v_mul_f32_e32 v106, v112, v54
	v_mul_f32_e32 v107, v112, v55
	v_cvt_scalef32_pk_fp4_f32 v113, v106, v107, 1.0 op_sel:[0,0,1,1]
	v_lshl_add_u64 v[114:115], v[108:109], 2, v[114:115]
	global_store_dword v[114:115], v113, off
	s_mov_b64 exec, s[24:25]
	s_mov_b32 s0, s22
	s_ashr_i32 s1, s0, 31
	s_lshl_b64 s[0:1], s[0:1], 9
	v_lshl_add_u64 v[104:105], s[0:1], 0, v[104:105]
	s_mov_b64 s[0:1], 0x400000
	v_cmp_gt_u64_e32 vcc, s[0:1], v[104:105]
	s_and_saveexec_b64 s[24:25], vcc
	s_mov_b64 s[0:1], 0x1fffff
	v_cmp_lt_u64_e32 vcc, s[0:1], v[104:105]
	s_mov_b32 s0, 0xffe00000
	s_mov_b32 s1, -1
	v_lshl_add_u64 v[106:107], v[104:105], 0, s[0:1]
	v_cndmask_b32_e32 v108, v104, v106, vcc
	v_cndmask_b32_e32 v109, v105, v107, vcc
	v_mov_b32_e32 v106, 0x42400000
	v_mov_b32_e32 v107, 0x40880000
	v_cndmask_b32_e32 v112, v106, v107, vcc
	v_mov_b32_e32 v106, 0xf4e0000
	v_mov_b32_e32 v107, 0x114e0000
	v_cndmask_b32_e32 v106, v106, v107, vcc
	v_mov_b32_e32 v107, v1
	v_lshl_add_u64 v[114:115], s[18:19], 0, v[106:107]
	v_mul_f32_e32 v106, v56, v112
	v_mul_f32_e32 v107, v57, v112
	v_mov_b32_e32 v113, v1
	v_cvt_scalef32_pk_fp4_f32 v113, v106, v107, 1.0
	v_mul_f32_e32 v106, v58, v112
	v_mul_f32_e32 v107, v59, v112
	v_cvt_scalef32_pk_fp4_f32 v113, v106, v107, 1.0 op_sel:[0,0,1,0]
	v_mul_f32_e32 v106, v112, v60
; DEVI void norm_phase(const Params& p, int layer, int which, bool first) {
;     ...
;       const float* s = (second ? sv : su) + j * 8;
;       const f32x4 a = *(const f32x4*)s, b = *(const f32x4*)(s + 4);
;       if (second) {
;         unsigned w = 0;
;         w = __builtin_amdgcn_cvt_scalef32_pk_fp4_f32(w, a[0] * 4.25f, a[1] * 4.25f, 1.0f, 0);
;         w = __builtin_amdgcn_cvt_scalef32_pk_fp4_f32(w, a[2] * 4.25f, a[3] * 4.25f, 1.0f, 1);
;         w = __builtin_amdgcn_cvt_scalef32_pk_fp4_f32(w, b[0] * 4.25f, b[1] * 4.25f, 1.0f, 2);
;         w = __builtin_amdgcn_cvt_scalef32_pk_fp4_f32(w, b[2] * 4.25f, b[3] * 4.25f, 1.0f, 3);
;         *(unsigned*)(dv + j * 4) = w;
;       } else {
;         unsigned w = 0;
;         w = __builtin_amdgcn_cvt_scalef32_pk_fp4_f32(w, a[0] * 48.f, a[1] * 48.f, 1.0f, 0);
;         w = __builtin_amdgcn_cvt_scalef32_pk_fp4_f32(w, a[2] * 48.f, a[3] * 48.f, 1.0f, 1);
;         w = __builtin_amdgcn_cvt_scalef32_pk_fp4_f32(w, b[0] * 48.f, b[1] * 48.f, 1.0f, 2);
;         w = __builtin_amdgcn_cvt_scalef32_pk_fp4_f32(w, b[2] * 48.f, b[3] * 48.f, 1.0f, 3);
;         *(unsigned*)(du + j * 4) = w;
	v_mul_f32_e32 v107, v112, v61
	v_cvt_scalef32_pk_fp4_f32 v113, v106, v107, 1.0 op_sel:[0,0,0,1]
	v_mul_f32_e32 v106, v112, v62
	v_mul_f32_e32 v107, v112, v63
	v_cvt_scalef32_pk_fp4_f32 v113, v106, v107, 1.0 op_sel:[0,0,1,1]
	v_lshl_add_u64 v[114:115], v[108:109], 2, v[114:115]
	global_store_dword v[114:115], v113, off
	s_mov_b64 exec, s[24:25]
	s_mov_b32 s0, s22
	s_ashr_i32 s1, s0, 31
	s_lshl_b64 s[0:1], s[0:1], 9
	v_lshl_add_u64 v[104:105], s[0:1], 0, v[104:105]
	s_mov_b64 s[0:1], 0x400000
	v_cmp_gt_u64_e32 vcc, s[0:1], v[104:105]
	s_and_saveexec_b64 s[24:25], vcc
	s_mov_b64 s[0:1], 0x1fffff
	v_cmp_lt_u64_e32 vcc, s[0:1], v[104:105]
	s_mov_b32 s0, 0xffe00000
	s_mov_b32 s1, -1
	v_lshl_add_u64 v[106:107], v[104:105], 0, s[0:1]
	v_cndmask_b32_e32 v108, v104, v106, vcc
	v_cndmask_b32_e32 v109, v105, v107, vcc
	v_mov_b32_e32 v106, 0x42400000
	v_mov_b32_e32 v107, 0x40880000
	v_cndmask_b32_e32 v112, v106, v107, vcc
	v_mov_b32_e32 v106, 0xf4e0000
	v_mov_b32_e32 v107, 0x114e0000
	v_cndmask_b32_e32 v106, v106, v107, vcc
	v_mov_b32_e32 v107, v1
	v_lshl_add_u64 v[114:115], s[18:19], 0, v[106:107]
	v_mul_f32_e32 v106, v64, v112
	v_mul_f32_e32 v107, v65, v112
	v_mov_b32_e32 v113, v1
	v_cvt_scalef32_pk_fp4_f32 v113, v106, v107, 1.0
	v_mul_f32_e32 v106, v66, v112
	v_mul_f32_e32 v107, v67, v112
	v_cvt_scalef32_pk_fp4_f32 v113, v106, v107, 1.0 op_sel:[0,0,1,0]
	v_mul_f32_e32 v106, v112, v68
	v_mul_f32_e32 v107, v112, v69
	v_cvt_scalef32_pk_fp4_f32 v113, v106, v107, 1.0 op_sel:[0,0,0,1]
	v_mul_f32_e32 v106, v112, v70
	v_mul_f32_e32 v107, v112, v71
	v_cvt_scalef32_pk_fp4_f32 v113, v106, v107, 1.0 op_sel:[0,0,1,1]
	v_lshl_add_u64 v[114:115], v[108:109], 2, v[114:115]
	global_store_dword v[114:115], v113, off
	s_mov_b64 exec, s[24:25]
	s_mov_b32 s0, s22
	s_ashr_i32 s1, s0, 31
	s_lshl_b64 s[0:1], s[0:1], 9
	v_lshl_add_u64 v[104:105], s[0:1], 0, v[104:105]
	s_mov_b64 s[0:1], 0x400000
	v_cmp_gt_u64_e32 vcc, s[0:1], v[104:105]
	s_and_saveexec_b64 s[24:25], vcc
	s_mov_b64 s[0:1], 0x1fffff
	v_cmp_lt_u64_e32 vcc, s[0:1], v[104:105]
	s_mov_b32 s0, 0xffe00000
	s_mov_b32 s1, -1
	v_lshl_add_u64 v[106:107], v[104:105], 0, s[0:1]
	v_cndmask_b32_e32 v108, v104, v106, vcc
	v_cndmask_b32_e32 v109, v105, v107, vcc
	v_mov_b32_e32 v106, 0x42400000
	v_mov_b32_e32 v107, 0x40880000
	v_cndmask_b32_e32 v112, v106, v107, vcc
	v_mov_b32_e32 v106, 0xf4e0000
	v_mov_b32_e32 v107, 0x114e0000
	v_cndmask_b32_e32 v106, v106, v107, vcc
	v_mov_b32_e32 v107, v1
	v_lshl_add_u64 v[114:115], s[18:19], 0, v[106:107]
	v_mul_f32_e32 v106, v72, v112
	v_mul_f32_e32 v107, v73, v112
	v_mov_b32_e32 v113, v1
	v_cvt_scalef32_pk_fp4_f32 v113, v106, v107, 1.0
	v_mul_f32_e32 v106, v74, v112
	v_mul_f32_e32 v107, v75, v112
	v_cvt_scalef32_pk_fp4_f32 v113, v106, v107, 1.0 op_sel:[0,0,1,0]
	v_mul_f32_e32 v106, v112, v76
	v_mul_f32_e32 v107, v112, v77
	v_cvt_scalef32_pk_fp4_f32 v113, v106, v107, 1.0 op_sel:[0,0,0,1]
	v_mul_f32_e32 v106, v112, v78
	v_mul_f32_e32 v107, v112, v79
	v_cvt_scalef32_pk_fp4_f32 v113, v106, v107, 1.0 op_sel:[0,0,1,1]
	v_lshl_add_u64 v[114:115], v[108:109], 2, v[114:115]
	global_store_dword v[114:115], v113, off
	s_mov_b64 exec, s[24:25]
	s_mov_b32 s0, s22
	s_ashr_i32 s1, s0, 31
	s_lshl_b64 s[0:1], s[0:1], 9
	v_lshl_add_u64 v[104:105], s[0:1], 0, v[104:105]
	s_mov_b64 s[0:1], 0x400000
	v_cmp_gt_u64_e32 vcc, s[0:1], v[104:105]
	s_and_saveexec_b64 s[24:25], vcc
	s_mov_b64 s[0:1], 0x1fffff
	v_cmp_lt_u64_e32 vcc, s[0:1], v[104:105]
	s_mov_b32 s0, 0xffe00000
	s_mov_b32 s1, -1
	v_lshl_add_u64 v[106:107], v[104:105], 0, s[0:1]
	v_cndmask_b32_e32 v108, v104, v106, vcc
	v_cndmask_b32_e32 v109, v105, v107, vcc
	v_mov_b32_e32 v106, 0x42400000
	v_mov_b32_e32 v107, 0x40880000
	v_cndmask_b32_e32 v112, v106, v107, vcc
	v_mov_b32_e32 v106, 0xf4e0000
	v_mov_b32_e32 v107, 0x114e0000
	v_cndmask_b32_e32 v106, v106, v107, vcc
; DEVI int ltid() { int t = threadIdx.x; asm volatile("" : "+v"(t)); return t; }
; DEVI int lbid() { int t = blockIdx.x; asm volatile("" : "+s"(t)); return t; }
; DEVI int lgdim() { int t = gridDim.x; asm volatile("" : "+s"(t)); return t; }
; DEVI void norm_phase(const Params& p, int layer, int which, bool first) {
;     ...
;     for (size_t i = (size_t)lbid() * 512 + ltid(); i < 2 * n8; i += (size_t)lgdim() * 512) {
;       const bool second = i >= n8; const size_t j = second ? i - n8 : i;
;       const float* s = (second ? sv : su) + j * 8;
;       const f32x4 a = *(const f32x4*)s, b = *(const f32x4*)(s + 4);
;       if (second) {
;         unsigned w = 0;
;         w = __builtin_amdgcn_cvt_scalef32_pk_fp4_f32(w, a[0] * 4.25f, a[1] * 4.25f, 1.0f, 0);
;         w = __builtin_amdgcn_cvt_scalef32_pk_fp4_f32(w, a[2] * 4.25f, a[3] * 4.25f, 1.0f, 1);
;         w = __builtin_amdgcn_cvt_scalef32_pk_fp4_f32(w, b[0] * 4.25f, b[1] * 4.25f, 1.0f, 2);
;         w = __builtin_amdgcn_cvt_scalef32_pk_fp4_f32(w, b[2] * 4.25f, b[3] * 4.25f, 1.0f, 3);
;         *(unsigned*)(dv + j * 4) = w;
;       } else {
;         unsigned w = 0;
;         w = __builtin_amdgcn_cvt_scalef32_pk_fp4_f32(w, a[0] * 48.f, a[1] * 48.f, 1.0f, 0);
;         w = __builtin_amdgcn_cvt_scalef32_pk_fp4_f32(w, a[2] * 48.f, a[3] * 48.f, 1.0f, 1);
;         w = __builtin_amdgcn_cvt_scalef32_pk_fp4_f32(w, b[0] * 48.f, b[1] * 48.f, 1.0f, 2);
;         w = __builtin_amdgcn_cvt_scalef32_pk_fp4_f32(w, b[2] * 48.f, b[3] * 48.f, 1.0f, 3);
;         *(unsigned*)(du + j * 4) = w;
;       }
;     }
	v_mov_b32_e32 v107, v1
	v_lshl_add_u64 v[114:115], s[18:19], 0, v[106:107]
	v_mul_f32_e32 v106, v80, v112
	v_mul_f32_e32 v107, v81, v112
	v_mov_b32_e32 v113, v1
	v_cvt_scalef32_pk_fp4_f32 v113, v106, v107, 1.0
	v_mul_f32_e32 v106, v82, v112
	v_mul_f32_e32 v107, v83, v112
	v_cvt_scalef32_pk_fp4_f32 v113, v106, v107, 1.0 op_sel:[0,0,1,0]
	v_mul_f32_e32 v106, v112, v84
	v_mul_f32_e32 v107, v112, v85
	v_cvt_scalef32_pk_fp4_f32 v113, v106, v107, 1.0 op_sel:[0,0,0,1]
	v_mul_f32_e32 v106, v112, v86
	v_mul_f32_e32 v107, v112, v87
	v_cvt_scalef32_pk_fp4_f32 v113, v106, v107, 1.0 op_sel:[0,0,1,1]
	v_lshl_add_u64 v[114:115], v[108:109], 2, v[114:115]
	global_store_dword v[114:115], v113, off
	s_mov_b64 exec, s[24:25]
	s_mov_b32 s0, s22
	s_ashr_i32 s1, s0, 31
	s_lshl_b64 s[0:1], s[0:1], 9
	v_lshl_add_u64 v[104:105], s[0:1], 0, v[104:105]
	s_mov_b64 s[0:1], 0x400000
	v_cmp_gt_u64_e32 vcc, s[0:1], v[104:105]
	s_and_saveexec_b64 s[24:25], vcc
	s_mov_b64 s[0:1], 0x1fffff
	v_cmp_lt_u64_e32 vcc, s[0:1], v[104:105]
	s_mov_b32 s0, 0xffe00000
	s_mov_b32 s1, -1
	v_lshl_add_u64 v[106:107], v[104:105], 0, s[0:1]
	v_cndmask_b32_e32 v108, v104, v106, vcc
	v_cndmask_b32_e32 v109, v105, v107, vcc
	v_mov_b32_e32 v106, 0x42400000
	v_mov_b32_e32 v107, 0x40880000
	v_cndmask_b32_e32 v112, v106, v107, vcc
	v_mov_b32_e32 v106, 0xf4e0000
	v_mov_b32_e32 v107, 0x114e0000
	v_cndmask_b32_e32 v106, v106, v107, vcc
	v_mov_b32_e32 v107, v1
	v_lshl_add_u64 v[114:115], s[18:19], 0, v[106:107]
	v_mul_f32_e32 v106, v88, v112
	v_mul_f32_e32 v107, v89, v112
	v_mov_b32_e32 v113, v1
	v_cvt_scalef32_pk_fp4_f32 v113, v106, v107, 1.0
	v_mul_f32_e32 v106, v90, v112
	v_mul_f32_e32 v107, v91, v112
	v_cvt_scalef32_pk_fp4_f32 v113, v106, v107, 1.0 op_sel:[0,0,1,0]
	v_mul_f32_e32 v106, v112, v92
	v_mul_f32_e32 v107, v112, v93
	v_cvt_scalef32_pk_fp4_f32 v113, v106, v107, 1.0 op_sel:[0,0,0,1]
	v_mul_f32_e32 v106, v112, v94
	v_mul_f32_e32 v107, v112, v95
	v_cvt_scalef32_pk_fp4_f32 v113, v106, v107, 1.0 op_sel:[0,0,1,1]
	v_lshl_add_u64 v[114:115], v[108:109], 2, v[114:115]
	global_store_dword v[114:115], v113, off
	s_mov_b64 exec, s[24:25]
	s_mov_b32 s0, s22
	s_ashr_i32 s1, s0, 31
	s_lshl_b64 s[0:1], s[0:1], 9
	v_lshl_add_u64 v[104:105], s[0:1], 0, v[104:105]
	s_mov_b64 s[0:1], 0x400000
	v_cmp_gt_u64_e32 vcc, s[0:1], v[104:105]
	s_and_saveexec_b64 s[24:25], vcc
	s_mov_b64 s[0:1], 0x1fffff
	v_cmp_lt_u64_e32 vcc, s[0:1], v[104:105]
	s_mov_b32 s0, 0xffe00000
	s_mov_b32 s1, -1
	v_lshl_add_u64 v[106:107], v[104:105], 0, s[0:1]
	v_cndmask_b32_e32 v108, v104, v106, vcc
	v_cndmask_b32_e32 v109, v105, v107, vcc
	v_mov_b32_e32 v106, 0x42400000
	v_mov_b32_e32 v107, 0x40880000
	v_cndmask_b32_e32 v112, v106, v107, vcc
	v_mov_b32_e32 v106, 0xf4e0000
	v_mov_b32_e32 v107, 0x114e0000
	v_cndmask_b32_e32 v106, v106, v107, vcc
	v_mov_b32_e32 v107, v1
	v_lshl_add_u64 v[114:115], s[18:19], 0, v[106:107]
	v_mul_f32_e32 v106, v96, v112
	v_mul_f32_e32 v107, v97, v112
	v_mov_b32_e32 v113, v1
	v_cvt_scalef32_pk_fp4_f32 v113, v106, v107, 1.0
	v_mul_f32_e32 v106, v98, v112
	v_mul_f32_e32 v107, v99, v112
	v_cvt_scalef32_pk_fp4_f32 v113, v106, v107, 1.0 op_sel:[0,0,1,0]
	v_mul_f32_e32 v106, v112, v100
	v_mul_f32_e32 v107, v112, v101
	v_cvt_scalef32_pk_fp4_f32 v113, v106, v107, 1.0 op_sel:[0,0,0,1]
	v_mul_f32_e32 v106, v112, v102
	v_mul_f32_e32 v107, v112, v103
	v_cvt_scalef32_pk_fp4_f32 v113, v106, v107, 1.0 op_sel:[0,0,1,1]
	v_lshl_add_u64 v[114:115], v[108:109], 2, v[114:115]
	global_store_dword v[114:115], v113, off
	s_mov_b64 exec, s[24:25]
	s_mov_b32 s0, s22
	s_ashr_i32 s1, s0, 31
	s_lshl_b64 s[0:1], s[0:1], 9
	v_lshl_add_u64 v[104:105], s[0:1], 0, v[104:105]
	v_mov_b64_e32 v[2:3], v[104:105]
	s_mov_b64 s[0:1], 0x3fffff
	v_cmp_lt_u64_e32 vcc, s[0:1], v[2:3]
	s_or_b64 s[16:17], vcc, s[16:17]
	s_andn2_b64 exec, exec, s[16:17]
	s_cbranch_execnz .LBB0_355
